# rope phase: each row's q/k regions first touched with fully coalesced loads so memory sees whole-line requests before the strided 16-byte-per-lane loads
# baseline (speedup 1.0000x reference)
.LBB0_992:
	s_ashr_i32 s3, s2, 31
	s_lshl_b64 s[4:5], s[2:3], 13
	v_readlane_b32 s20, v253, 56
	v_readlane_b32 s21, v253, 57
	s_add_u32 s20, s20, s4
	s_addc_u32 s21, s21, s5
	v_lshlrev_b32_e32 v120, 4, v58
	global_load_dwordx4 v[100:103], v120, s[20:21]
	global_load_dwordx4 v[104:107], v120, s[20:21] offset:1024
	global_load_dwordx4 v[108:111], v120, s[20:21] offset:2048
	s_add_u32 s20, s20, 0x1000
	s_addc_u32 s21, s21, 0
	global_load_dwordx4 v[112:115], v120, s[20:21] offset:1536
	global_load_dwordx4 v[116:119], v120, s[20:21] offset:2560
	s_mul_hi_i32 s3, s2, 0x38e38e39
	s_lshr_b32 s8, s3, 31
	s_ashr_i32 s3, s3, 9
	s_add_i32 s3, s3, s8
	s_mulk_i32 s3, 0x900
	s_sub_i32 s3, s2, s3
	s_cmpk_gt_i32 s3, 0xff
	s_cselect_b64 s[8:9], -1, 0
	s_add_i32 s10, s3, 0xffffff00
	s_ashr_i32 s10, s10, 6
	v_cvt_f32_i32_e32 v24, s10
	s_and_b32 s10, s3, 63
	s_cmpk_lt_i32 s3, 0x100
	v_cvt_f32_ubyte0_e32 v25, s10
	s_cbranch_scc1 .LBB0_996
	v_lshl_add_u64 v[16:17], v[10:11], 0, s[4:5]
	s_mov_b64 s[10:11], 0
	v_mov_b32_e32 v13, v70
	v_mov_b32_e32 v15, v58
